# GLA state scan: the 8 per-chunk decay loads issued together (one wait) instead of 8 serialized load+wait round trips
# speedup vs baseline: 1.0416x; 1.0041x over previous
; #define LAS __attribute__((address_space(3)))
; DI void gla_scan(const Params& p, int tid, LAS unsigned char* lds) {
;     float* UPD = (float*)(p.ws + WS_XB); const float* DEC = (const float*)(p.ws + WS_DEC);
;     LAS float* DL = (LAS float*)lds;
;     for (int e0 = blockIdx.x * 512; e0 < 16 * 8192; e0 += gridDim.x * 512) {
;         const int e = e0 + tid;
;         const int bh = e >> 13, idx = e & 8191, k = idx & 63, b = bh >> 2, h = bh & 3;
;         float* up0 = UPD + (size_t)((b * 64) << 2) * 8192 + (size_t)h * 8192 + idx; const float* dp0 = DEC + (((b * 64) << 2) + h) * 64;
; #pragma unroll
;         for (int q = 0; q < 8; ++q) { const int i = tid + q * 512; DL[i] = dp0[(i >> 6) * 4 * 64 + (i & 63)]; }
;         __syncthreads();
;         float S = 0.f;
; #pragma unroll
;         for (int n0 = 0; n0 < 64; n0 += 32) {
;             float u[32];
; #pragma unroll
;             for (int n = 0; n < 32; ++n) u[n] = up0[(size_t)(n0 + n) * 4 * 8192];
; #pragma unroll
;             for (int n = 0; n < 32; ++n) { up0[(size_t)(n0 + n) * 4 * 8192] = S; S = fmaf(DL[(n0 + n) * 64 + k], S, u[n]); }
.LBB0_369:
	v_add_u32_e32 v0, s2, v82
	s_waitcnt vmcnt(0)
	v_and_b32_e32 v24, 0x1fff, v0
	v_bfe_u32 v25, v0, 13, 2
	v_ashrrev_i32_e32 v0, 7, v0
	v_and_b32_e32 v18, 0xffffff00, v0
	v_ashrrev_i32_e32 v19, 31, v18
	v_or_b32_e32 v0, v18, v25
	v_lshlrev_b64 v[20:21], 15, v[18:19]
	v_lshlrev_b32_e32 v18, 6, v0
	v_ashrrev_i32_e32 v19, 31, v18
	v_lshl_add_u64 v[18:19], v[18:19], 2, s[4:5]
	v_lshl_add_u64 v[22:23], v[2:3], 2, v[18:19]
	flat_load_dword v140, v[22:23]
	v_lshl_add_u64 v[22:23], v[4:5], 2, v[18:19]
	s_mov_b32 s3, 0x20000
	s_add_i32 s2, s2, s6
	s_cmp_lt_i32 s2, 0x20000
	flat_load_dword v141, v[22:23]
	v_lshl_add_u64 v[22:23], v[6:7], 2, v[18:19]
	flat_load_dword v142, v[22:23]
	v_lshl_add_u64 v[22:23], v[8:9], 2, v[18:19]
	flat_load_dword v143, v[22:23]
	v_lshl_add_u64 v[22:23], v[10:11], 2, v[18:19]
	flat_load_dword v144, v[22:23]
	v_lshl_add_u64 v[22:23], v[12:13], 2, v[18:19]
	flat_load_dword v145, v[22:23]
	v_lshl_add_u64 v[22:23], v[14:15], 2, v[18:19]
	v_lshl_add_u64 v[18:19], v[16:17], 2, v[18:19]
	flat_load_dword v146, v[22:23]
	flat_load_dword v147, v[18:19]
	v_lshl_add_u64 v[18:19], s[0:1], 0, v[20:21]
	s_waitcnt vmcnt(0) lgkmcnt(0)
	ds_write_b32 v84, v140
	ds_write_b32 v84, v141 offset:2048
	ds_write_b32 v84, v142 offset:4096
	ds_write_b32 v84, v143 offset:6144
	ds_write_b32 v84, v144 offset:8192
	ds_write_b32 v84, v145 offset:10240
	ds_write_b32 v84, v146 offset:12288
	ds_write_b32 v84, v147 offset:14336
	v_lshlrev_b32_e32 v0, 15, v25
	v_lshl_add_u64 v[18:19], v[18:19], 0, v[0:1]
	v_lshlrev_b32_e32 v0, 2, v24
	v_lshl_add_u64 v[18:19], v[18:19], 0, v[0:1]
	s_waitcnt lgkmcnt(0)
	s_barrier
	flat_load_dword v54, v[18:19]
	v_add_co_u32_e32 v20, vcc, s3, v18
	s_mov_b32 s3, 0x40000
	s_nop 0
	v_addc_co_u32_e32 v21, vcc, 0, v19, vcc
	flat_load_dword v55, v[20:21]
	v_add_co_u32_e32 v22, vcc, s3, v18
	s_mov_b32 s3, 0x60000
	s_nop 0
	v_addc_co_u32_e32 v23, vcc, 0, v19, vcc
	flat_load_dword v85, v[22:23]
	v_add_co_u32_e32 v24, vcc, s3, v18
	s_mov_b32 s3, 0x80000
	s_nop 0
	v_addc_co_u32_e32 v25, vcc, 0, v19, vcc
	flat_load_dword v88, v[24:25]
	v_add_co_u32_e32 v26, vcc, s3, v18
	s_mov_b32 s3, 0xa0000
	s_nop 0
	v_addc_co_u32_e32 v27, vcc, 0, v19, vcc
	flat_load_dword v89, v[26:27]
	v_add_co_u32_e32 v28, vcc, s3, v18
	s_mov_b32 s3, 0xc0000
	s_nop 0
	v_addc_co_u32_e32 v29, vcc, 0, v19, vcc
	flat_load_dword v90, v[28:29]
	v_add_co_u32_e32 v30, vcc, s3, v18
	s_mov_b32 s3, 0xe0000
	s_nop 0
	v_addc_co_u32_e32 v31, vcc, 0, v19, vcc
	flat_load_dword v91, v[30:31]
	v_add_co_u32_e32 v32, vcc, s3, v18
	s_mov_b32 s3, 0x100000
	s_nop 0
	v_addc_co_u32_e32 v33, vcc, 0, v19, vcc
	flat_load_dword v92, v[32:33]
	v_add_co_u32_e32 v34, vcc, s3, v18
	s_mov_b32 s3, 0x120000
	s_nop 0
	v_addc_co_u32_e32 v35, vcc, 0, v19, vcc
	flat_load_dword v93, v[34:35]
	v_add_co_u32_e32 v36, vcc, s3, v18
	s_mov_b32 s3, 0x140000
	s_nop 0
	v_addc_co_u32_e32 v37, vcc, 0, v19, vcc
	flat_load_dword v94, v[36:37]
	v_add_co_u32_e32 v38, vcc, s3, v18
	s_mov_b32 s3, 0x160000
	s_nop 0
	v_addc_co_u32_e32 v39, vcc, 0, v19, vcc
	flat_load_dword v95, v[38:39]
	v_add_co_u32_e32 v40, vcc, s3, v18
	flat_store_dword v[18:19], v1
	ds_read_b32 v116, v83
	v_addc_co_u32_e32 v41, vcc, 0, v19, vcc
	flat_load_dword v96, v[40:41]
	s_mov_b32 s3, 0x180000
	v_add_co_u32_e32 v42, vcc, s3, v18
	s_mov_b32 s3, 0x1a0000
	s_nop 0
	v_addc_co_u32_e32 v43, vcc, 0, v19, vcc
	flat_load_dword v97, v[42:43]
	v_add_co_u32_e32 v44, vcc, s3, v18
	s_mov_b32 s3, 0x1c0000
	s_nop 0
	v_addc_co_u32_e32 v45, vcc, 0, v19, vcc
	s_waitcnt vmcnt(0) lgkmcnt(0)
	v_fmac_f32_e32 v54, 0, v116
	flat_store_dword v[20:21], v54
	ds_read_b32 v20, v83 offset:256
	flat_load_dword v98, v[44:45]
	v_add_co_u32_e32 v46, vcc, s3, v18
	s_mov_b32 s3, 0x1e0000
	s_waitcnt lgkmcnt(0)
	v_fmac_f32_e32 v55, v20, v54
	flat_store_dword v[22:23], v55
	ds_read_b32 v20, v83 offset:512
	v_addc_co_u32_e32 v47, vcc, 0, v19, vcc
	flat_load_dword v99, v[46:47]
	v_add_co_u32_e32 v48, vcc, s3, v18
	s_waitcnt lgkmcnt(0)
	v_fmac_f32_e32 v85, v20, v55
	flat_store_dword v[24:25], v85
	ds_read_b32 v20, v83 offset:768
	v_addc_co_u32_e32 v49, vcc, 0, v19, vcc
	flat_load_dword v100, v[48:49]
	s_mov_b32 s3, 0x200000
	s_waitcnt lgkmcnt(0)
	v_fmac_f32_e32 v88, v20, v85
	flat_store_dword v[26:27], v88
	ds_read_b32 v20, v83 offset:1024
	v_add_co_u32_e32 v50, vcc, s3, v18
	s_mov_b32 s3, 0x220000
	s_nop 0
	v_addc_co_u32_e32 v51, vcc, 0, v19, vcc
	s_waitcnt lgkmcnt(0)
	v_fmac_f32_e32 v89, v20, v88
	flat_store_dword v[28:29], v89
	ds_read_b32 v20, v83 offset:1280
	flat_load_dword v101, v[50:51]
	v_add_co_u32_e32 v52, vcc, s3, v18
	s_mov_b32 s3, 0x240000
	s_waitcnt lgkmcnt(0)
	v_fmac_f32_e32 v90, v20, v89
	flat_store_dword v[30:31], v90
	ds_read_b32 v20, v83 offset:1536
	v_addc_co_u32_e32 v53, vcc, 0, v19, vcc
	flat_load_dword v102, v[52:53]
	v_add_co_u32_e32 v56, vcc, s3, v18
	s_waitcnt lgkmcnt(0)
	v_fmac_f32_e32 v91, v20, v90
	flat_store_dword v[32:33], v91
	ds_read_b32 v20, v83 offset:1792
	v_addc_co_u32_e32 v57, vcc, 0, v19, vcc
	flat_load_dword v103, v[56:57]
	s_mov_b32 s3, 0x260000
	s_waitcnt lgkmcnt(0)
	v_fmac_f32_e32 v92, v20, v91
	flat_store_dword v[34:35], v92
	v_add_co_u32_e32 v58, vcc, s3, v18
	ds_read_b32 v20, v83 offset:2048
	s_nop 0
	v_addc_co_u32_e32 v59, vcc, 0, v19, vcc
	flat_load_dword v104, v[58:59]
	s_mov_b32 s3, 0x280000
	s_waitcnt lgkmcnt(0)
	v_fmac_f32_e32 v93, v20, v92
	flat_store_dword v[36:37], v93
	v_add_co_u32_e32 v60, vcc, s3, v18
	ds_read_b32 v20, v83 offset:2304
	s_nop 0
	v_addc_co_u32_e32 v61, vcc, 0, v19, vcc
	flat_load_dword v105, v[60:61]
	s_mov_b32 s3, 0x2a0000
	s_waitcnt lgkmcnt(0)
; DI void gla_scan(const Params& p, int tid, LAS unsigned char* lds) {
;     ...
;         for (int n0 = 0; n0 < 64; n0 += 32) {
;             float u[32];
; #pragma unroll
;             for (int n = 0; n < 32; ++n) u[n] = up0[(size_t)(n0 + n) * 4 * 8192];
; #pragma unroll
;             for (int n = 0; n < 32; ++n) { up0[(size_t)(n0 + n) * 4 * 8192] = S; S = fmaf(DL[(n0 + n) * 64 + k], S, u[n]); }
	v_fmac_f32_e32 v94, v20, v93
	flat_store_dword v[38:39], v94
	v_add_co_u32_e32 v62, vcc, s3, v18
	ds_read_b32 v20, v83 offset:2560
	s_nop 0
	v_addc_co_u32_e32 v63, vcc, 0, v19, vcc
	flat_load_dword v106, v[62:63]
	s_mov_b32 s3, 0x2c0000
	s_waitcnt lgkmcnt(0)
	v_fmac_f32_e32 v95, v20, v94
	flat_store_dword v[40:41], v95
	v_add_co_u32_e32 v64, vcc, s3, v18
	ds_read_b32 v20, v83 offset:2816
	s_nop 0
	v_addc_co_u32_e32 v65, vcc, 0, v19, vcc
	flat_load_dword v107, v[64:65]
	s_mov_b32 s3, 0x2e0000
	s_waitcnt lgkmcnt(0)
	v_fmac_f32_e32 v96, v20, v95
	flat_store_dword v[42:43], v96
	v_add_co_u32_e32 v66, vcc, s3, v18
	ds_read_b32 v20, v83 offset:3072
	s_nop 0
	v_addc_co_u32_e32 v67, vcc, 0, v19, vcc
	flat_load_dword v108, v[66:67]
	s_mov_b32 s3, 0x300000
	s_waitcnt lgkmcnt(0)
	v_fmac_f32_e32 v97, v20, v96
	flat_store_dword v[44:45], v97
	v_add_co_u32_e32 v68, vcc, s3, v18
	ds_read_b32 v20, v83 offset:3328
	s_nop 0
	v_addc_co_u32_e32 v69, vcc, 0, v19, vcc
	flat_load_dword v109, v[68:69]
	s_mov_b32 s3, 0x320000
	s_waitcnt vmcnt(0) lgkmcnt(0)
	v_fmac_f32_e32 v98, v20, v97
	flat_store_dword v[46:47], v98
	v_add_co_u32_e32 v70, vcc, s3, v18
	ds_read_b32 v20, v83 offset:3584
	s_nop 0
	v_addc_co_u32_e32 v71, vcc, 0, v19, vcc
	flat_load_dword v110, v[70:71]
	s_mov_b32 s3, 0x340000
	s_waitcnt lgkmcnt(0)
	v_fmac_f32_e32 v99, v20, v98
	flat_store_dword v[48:49], v99
	v_add_co_u32_e32 v72, vcc, s3, v18
	ds_read_b32 v20, v83 offset:3840
	s_nop 0
	v_addc_co_u32_e32 v73, vcc, 0, v19, vcc
	flat_load_dword v111, v[72:73]
	s_mov_b32 s3, 0x360000
	s_waitcnt lgkmcnt(0)
	v_fmac_f32_e32 v100, v20, v99
	flat_store_dword v[50:51], v100
	v_add_co_u32_e32 v74, vcc, s3, v18
	ds_read_b32 v20, v83 offset:4096
	s_nop 0
	v_addc_co_u32_e32 v75, vcc, 0, v19, vcc
	flat_load_dword v112, v[74:75]
	s_mov_b32 s3, 0x380000
	s_waitcnt lgkmcnt(0)
	v_fmac_f32_e32 v101, v20, v100
	flat_store_dword v[52:53], v101
	v_add_co_u32_e32 v76, vcc, s3, v18
	ds_read_b32 v20, v83 offset:4352
	s_nop 0
	v_addc_co_u32_e32 v77, vcc, 0, v19, vcc
	flat_load_dword v113, v[76:77]
	s_mov_b32 s3, 0x3a0000
	s_waitcnt lgkmcnt(0)
	v_fmac_f32_e32 v102, v20, v101
	flat_store_dword v[56:57], v102
	v_add_co_u32_e32 v78, vcc, s3, v18
	ds_read_b32 v20, v83 offset:4608
	s_nop 0
	v_addc_co_u32_e32 v79, vcc, 0, v19, vcc
	flat_load_dword v114, v[78:79]
	s_mov_b32 s3, 0x3c0000
	s_waitcnt lgkmcnt(0)
	v_fmac_f32_e32 v103, v20, v102
	flat_store_dword v[58:59], v103
	v_add_co_u32_e32 v80, vcc, s3, v18
	ds_read_b32 v20, v83 offset:4864
	s_nop 0
	v_addc_co_u32_e32 v81, vcc, 0, v19, vcc
	flat_load_dword v115, v[80:81]
	s_mov_b32 s3, 0x3e0000
	s_waitcnt lgkmcnt(0)
	v_fmac_f32_e32 v104, v20, v103
	flat_store_dword v[60:61], v104
	v_add_co_u32_e32 v86, vcc, s3, v18
	ds_read_b32 v20, v83 offset:5120
	s_nop 0
	v_addc_co_u32_e32 v87, vcc, 0, v19, vcc
	flat_load_dword v0, v[86:87]
	s_mov_b32 s3, 0x400000
	s_waitcnt lgkmcnt(0)
	v_fmac_f32_e32 v105, v20, v104
	flat_store_dword v[62:63], v105
	ds_read_b32 v20, v83 offset:5376
	s_waitcnt lgkmcnt(0)
	v_fmac_f32_e32 v106, v20, v105
	flat_store_dword v[64:65], v106
	ds_read_b32 v20, v83 offset:5632
	s_waitcnt lgkmcnt(0)
	v_fmac_f32_e32 v107, v20, v106
	flat_store_dword v[66:67], v107
	ds_read_b32 v20, v83 offset:5888
	s_waitcnt lgkmcnt(0)
	v_fmac_f32_e32 v108, v20, v107
	flat_store_dword v[68:69], v108
	ds_read_b32 v20, v83 offset:6144
	s_waitcnt lgkmcnt(0)
	v_fmac_f32_e32 v109, v20, v108
	flat_store_dword v[70:71], v109
	ds_read_b32 v20, v83 offset:6400
	s_waitcnt vmcnt(0) lgkmcnt(0)
	v_fmac_f32_e32 v110, v20, v109
	flat_store_dword v[72:73], v110
	ds_read_b32 v20, v83 offset:6656
	s_waitcnt lgkmcnt(0)
	v_fmac_f32_e32 v111, v20, v110
	flat_store_dword v[74:75], v111
	ds_read_b32 v20, v83 offset:6912
	s_waitcnt lgkmcnt(0)
	v_fmac_f32_e32 v112, v20, v111
	flat_store_dword v[76:77], v112
	ds_read_b32 v20, v83 offset:7168
	s_waitcnt lgkmcnt(0)
	v_fmac_f32_e32 v113, v20, v112
	flat_store_dword v[78:79], v113
	ds_read_b32 v20, v83 offset:7424
	s_waitcnt lgkmcnt(0)
	v_fmac_f32_e32 v114, v20, v113
	flat_store_dword v[80:81], v114
	ds_read_b32 v20, v83 offset:7680
	s_waitcnt lgkmcnt(0)
	v_fmac_f32_e32 v115, v20, v114
	flat_store_dword v[86:87], v115
	ds_read_b32 v20, v83 offset:7936
	s_waitcnt lgkmcnt(0)
	v_fmac_f32_e32 v0, v20, v115
	v_add_co_u32_e32 v20, vcc, s3, v18
	s_mov_b32 s3, 0x420000
	s_nop 0
	v_addc_co_u32_e32 v21, vcc, 0, v19, vcc
	flat_load_dword v85, v[20:21]
	v_add_co_u32_e32 v22, vcc, s3, v18
	s_mov_b32 s3, 0x440000
	s_nop 0
	v_addc_co_u32_e32 v23, vcc, 0, v19, vcc
	flat_load_dword v86, v[22:23]
	v_add_co_u32_e32 v24, vcc, s3, v18
	s_mov_b32 s3, 0x460000
	s_nop 0
	v_addc_co_u32_e32 v25, vcc, 0, v19, vcc
	flat_load_dword v87, v[24:25]
	v_add_co_u32_e32 v26, vcc, s3, v18
	s_mov_b32 s3, 0x480000
	s_nop 0
	v_addc_co_u32_e32 v27, vcc, 0, v19, vcc
	flat_load_dword v88, v[26:27]
	v_add_co_u32_e32 v28, vcc, s3, v18
	s_mov_b32 s3, 0x4a0000
	s_nop 0
	v_addc_co_u32_e32 v29, vcc, 0, v19, vcc
	flat_load_dword v89, v[28:29]
	v_add_co_u32_e32 v30, vcc, s3, v18
	s_mov_b32 s3, 0x4c0000
	s_nop 0
	v_addc_co_u32_e32 v31, vcc, 0, v19, vcc
	flat_load_dword v90, v[30:31]
	v_add_co_u32_e32 v32, vcc, s3, v18
	s_mov_b32 s3, 0x4e0000
	s_nop 0
	v_addc_co_u32_e32 v33, vcc, 0, v19, vcc
	flat_load_dword v91, v[32:33]
	v_add_co_u32_e32 v34, vcc, s3, v18
	s_mov_b32 s3, 0x500000
	s_nop 0
	v_addc_co_u32_e32 v35, vcc, 0, v19, vcc
	flat_load_dword v92, v[34:35]
	v_add_co_u32_e32 v36, vcc, s3, v18
	s_mov_b32 s3, 0x520000
	s_nop 0
	v_addc_co_u32_e32 v37, vcc, 0, v19, vcc
	flat_load_dword v93, v[36:37]
	v_add_co_u32_e32 v38, vcc, s3, v18
	s_mov_b32 s3, 0x540000
	s_nop 0
	v_addc_co_u32_e32 v39, vcc, 0, v19, vcc
	flat_load_dword v94, v[38:39]
	v_add_co_u32_e32 v40, vcc, s3, v18
	s_mov_b32 s3, 0x560000
	s_nop 0
	v_addc_co_u32_e32 v41, vcc, 0, v19, vcc
	flat_load_dword v95, v[40:41]
	v_add_co_u32_e32 v42, vcc, s3, v18
	flat_store_dword v[20:21], v0
	ds_read_b32 v20, v83 offset:8192
	v_addc_co_u32_e32 v43, vcc, 0, v19, vcc
	flat_load_dword v96, v[42:43]
	s_mov_b32 s3, 0x580000
	v_add_co_u32_e32 v44, vcc, s3, v18
	s_mov_b32 s3, 0x5a0000
	s_nop 0
	v_addc_co_u32_e32 v45, vcc, 0, v19, vcc
	flat_load_dword v97, v[44:45]
	v_add_co_u32_e32 v46, vcc, s3, v18
	s_mov_b32 s3, 0x5c0000
	s_nop 0
	v_addc_co_u32_e32 v47, vcc, 0, v19, vcc
	s_waitcnt vmcnt(0) lgkmcnt(0)
; DI void gla_scan(const Params& p, int tid, LAS unsigned char* lds) {
;     ...
;         for (int n0 = 0; n0 < 64; n0 += 32) {
;             float u[32];
; #pragma unroll
;             for (int n = 0; n < 32; ++n) u[n] = up0[(size_t)(n0 + n) * 4 * 8192];
; #pragma unroll
;             for (int n = 0; n < 32; ++n) { up0[(size_t)(n0 + n) * 4 * 8192] = S; S = fmaf(DL[(n0 + n) * 64 + k], S, u[n]); }
;         }
;         __syncthreads();
	v_fmac_f32_e32 v85, v20, v0
	flat_store_dword v[22:23], v85
	ds_read_b32 v0, v83 offset:8448
	flat_load_dword v98, v[46:47]
	v_add_co_u32_e32 v48, vcc, s3, v18
	s_mov_b32 s3, 0x5e0000
	s_waitcnt lgkmcnt(0)
	v_fmac_f32_e32 v86, v0, v85
	flat_store_dword v[24:25], v86
	ds_read_b32 v0, v83 offset:8704
	v_addc_co_u32_e32 v49, vcc, 0, v19, vcc
	flat_load_dword v99, v[48:49]
	v_add_co_u32_e32 v50, vcc, s3, v18
	s_waitcnt lgkmcnt(0)
	v_fmac_f32_e32 v87, v0, v86
	flat_store_dword v[26:27], v87
	ds_read_b32 v0, v83 offset:8960
	v_addc_co_u32_e32 v51, vcc, 0, v19, vcc
	flat_load_dword v100, v[50:51]
	s_mov_b32 s3, 0x600000
	s_waitcnt lgkmcnt(0)
	v_fmac_f32_e32 v88, v0, v87
	flat_store_dword v[28:29], v88
	ds_read_b32 v0, v83 offset:9216
	v_add_co_u32_e32 v52, vcc, s3, v18
	s_mov_b32 s3, 0x620000
	s_nop 0
	v_addc_co_u32_e32 v53, vcc, 0, v19, vcc
	s_waitcnt lgkmcnt(0)
	v_fmac_f32_e32 v89, v0, v88
	flat_store_dword v[30:31], v89
	ds_read_b32 v0, v83 offset:9472
	flat_load_dword v101, v[52:53]
	v_add_co_u32_e32 v54, vcc, s3, v18
	s_mov_b32 s3, 0x640000
	s_waitcnt lgkmcnt(0)
	v_fmac_f32_e32 v90, v0, v89
	flat_store_dword v[32:33], v90
	ds_read_b32 v0, v83 offset:9728
	v_addc_co_u32_e32 v55, vcc, 0, v19, vcc
	flat_load_dword v102, v[54:55]
	v_add_co_u32_e32 v56, vcc, s3, v18
	s_waitcnt lgkmcnt(0)
	v_fmac_f32_e32 v91, v0, v90
	flat_store_dword v[34:35], v91
	ds_read_b32 v0, v83 offset:9984
	v_addc_co_u32_e32 v57, vcc, 0, v19, vcc
	flat_load_dword v103, v[56:57]
	s_mov_b32 s3, 0x660000
	s_waitcnt lgkmcnt(0)
	v_fmac_f32_e32 v92, v0, v91
	flat_store_dword v[36:37], v92
	v_add_co_u32_e32 v58, vcc, s3, v18
	ds_read_b32 v0, v83 offset:10240
	s_nop 0
	v_addc_co_u32_e32 v59, vcc, 0, v19, vcc
	flat_load_dword v104, v[58:59]
	s_mov_b32 s3, 0x680000
	s_waitcnt lgkmcnt(0)
	v_fmac_f32_e32 v93, v0, v92
	flat_store_dword v[38:39], v93
	v_add_co_u32_e32 v60, vcc, s3, v18
	ds_read_b32 v0, v83 offset:10496
	s_nop 0
	v_addc_co_u32_e32 v61, vcc, 0, v19, vcc
	flat_load_dword v105, v[60:61]
	s_mov_b32 s3, 0x6a0000
	s_waitcnt lgkmcnt(0)
	v_fmac_f32_e32 v94, v0, v93
	flat_store_dword v[40:41], v94
	v_add_co_u32_e32 v62, vcc, s3, v18
	ds_read_b32 v0, v83 offset:10752
	s_nop 0
	v_addc_co_u32_e32 v63, vcc, 0, v19, vcc
	flat_load_dword v106, v[62:63]
	s_mov_b32 s3, 0x6c0000
	s_waitcnt lgkmcnt(0)
	v_fmac_f32_e32 v95, v0, v94
	flat_store_dword v[42:43], v95
	v_add_co_u32_e32 v64, vcc, s3, v18
	ds_read_b32 v0, v83 offset:11008
	s_nop 0
	v_addc_co_u32_e32 v65, vcc, 0, v19, vcc
	flat_load_dword v107, v[64:65]
	s_mov_b32 s3, 0x6e0000
	s_waitcnt lgkmcnt(0)
	v_fmac_f32_e32 v96, v0, v95
	flat_store_dword v[44:45], v96
	v_add_co_u32_e32 v66, vcc, s3, v18
	ds_read_b32 v0, v83 offset:11264
	s_nop 0
	v_addc_co_u32_e32 v67, vcc, 0, v19, vcc
	flat_load_dword v108, v[66:67]
	s_mov_b32 s3, 0x700000
	s_waitcnt lgkmcnt(0)
	v_fmac_f32_e32 v97, v0, v96
	flat_store_dword v[46:47], v97
	v_add_co_u32_e32 v68, vcc, s3, v18
	ds_read_b32 v0, v83 offset:11520
	s_nop 0
	v_addc_co_u32_e32 v69, vcc, 0, v19, vcc
	flat_load_dword v109, v[68:69]
	s_mov_b32 s3, 0x720000
	s_waitcnt vmcnt(0) lgkmcnt(0)
	v_fmac_f32_e32 v98, v0, v97
	flat_store_dword v[48:49], v98
	v_add_co_u32_e32 v70, vcc, s3, v18
	ds_read_b32 v0, v83 offset:11776
	s_nop 0
	v_addc_co_u32_e32 v71, vcc, 0, v19, vcc
	flat_load_dword v110, v[70:71]
	s_mov_b32 s3, 0x740000
	s_waitcnt lgkmcnt(0)
	v_fmac_f32_e32 v99, v0, v98
	flat_store_dword v[50:51], v99
	v_add_co_u32_e32 v72, vcc, s3, v18
	ds_read_b32 v0, v83 offset:12032
	s_nop 0
	v_addc_co_u32_e32 v73, vcc, 0, v19, vcc
	flat_load_dword v111, v[72:73]
	s_mov_b32 s3, 0x760000
	s_waitcnt lgkmcnt(0)
	v_fmac_f32_e32 v100, v0, v99
	flat_store_dword v[52:53], v100
	v_add_co_u32_e32 v74, vcc, s3, v18
	ds_read_b32 v0, v83 offset:12288
	s_nop 0
	v_addc_co_u32_e32 v75, vcc, 0, v19, vcc
	flat_load_dword v112, v[74:75]
	s_mov_b32 s3, 0x780000
	s_waitcnt lgkmcnt(0)
	v_fmac_f32_e32 v101, v0, v100
	flat_store_dword v[54:55], v101
	v_add_co_u32_e32 v76, vcc, s3, v18
	ds_read_b32 v0, v83 offset:12544
	s_nop 0
	v_addc_co_u32_e32 v77, vcc, 0, v19, vcc
	flat_load_dword v113, v[76:77]
	s_mov_b32 s3, 0x7a0000
	s_waitcnt lgkmcnt(0)
	v_fmac_f32_e32 v102, v0, v101
	flat_store_dword v[56:57], v102
	v_add_co_u32_e32 v78, vcc, s3, v18
	ds_read_b32 v0, v83 offset:12800
	s_nop 0
	v_addc_co_u32_e32 v79, vcc, 0, v19, vcc
	flat_load_dword v114, v[78:79]
	s_mov_b32 s3, 0x7c0000
	s_waitcnt lgkmcnt(0)
	v_fmac_f32_e32 v103, v0, v102
	flat_store_dword v[58:59], v103
	v_add_co_u32_e32 v80, vcc, s3, v18
	ds_read_b32 v0, v83 offset:13056
	s_nop 0
	v_addc_co_u32_e32 v81, vcc, 0, v19, vcc
	flat_load_dword v115, v[80:81]
	v_add_co_u32_e32 v18, vcc, 0x7e0000, v18
	s_waitcnt lgkmcnt(0)
	v_fmac_f32_e32 v104, v0, v103
	flat_store_dword v[60:61], v104
	ds_read_b32 v0, v83 offset:13312
	v_addc_co_u32_e32 v19, vcc, 0, v19, vcc
	s_waitcnt lgkmcnt(0)
	v_fmac_f32_e32 v105, v0, v104
	flat_store_dword v[62:63], v105
	ds_read_b32 v0, v83 offset:13568
	s_waitcnt lgkmcnt(0)
	v_fmac_f32_e32 v106, v0, v105
	flat_store_dword v[64:65], v106
	ds_read_b32 v0, v83 offset:13824
	s_waitcnt lgkmcnt(0)
	v_fmac_f32_e32 v107, v0, v106
	flat_store_dword v[66:67], v107
	ds_read_b32 v0, v83 offset:14080
	s_waitcnt lgkmcnt(0)
	v_fmac_f32_e32 v108, v0, v107
	flat_store_dword v[68:69], v108
	ds_read_b32 v0, v83 offset:14336
	s_waitcnt lgkmcnt(0)
	v_fmac_f32_e32 v109, v0, v108
	flat_store_dword v[70:71], v109
	ds_read_b32 v0, v83 offset:14592
	s_waitcnt vmcnt(0) lgkmcnt(0)
	v_fmac_f32_e32 v110, v0, v109
	flat_store_dword v[72:73], v110
	ds_read_b32 v0, v83 offset:14848
	s_waitcnt lgkmcnt(0)
	v_fmac_f32_e32 v111, v0, v110
	flat_store_dword v[74:75], v111
	ds_read_b32 v0, v83 offset:15104
	s_waitcnt lgkmcnt(0)
	v_fmac_f32_e32 v112, v0, v111
	flat_store_dword v[76:77], v112
	ds_read_b32 v0, v83 offset:15360
	s_waitcnt lgkmcnt(0)
	v_fmac_f32_e32 v113, v0, v112
	flat_store_dword v[78:79], v113
	ds_read_b32 v0, v83 offset:15616
	s_waitcnt lgkmcnt(0)
	v_fmac_f32_e32 v114, v0, v113
	flat_store_dword v[80:81], v114
	ds_read_b32 v0, v83 offset:15872
	s_waitcnt lgkmcnt(0)
	v_fmac_f32_e32 v115, v0, v114
	flat_store_dword v[18:19], v115
	s_waitcnt lgkmcnt(0)
	s_barrier
	s_cbranch_scc1 .LBB0_369
